# v49 + scan transpose-reads + scan unpacked muls + attention max chains + relaxed post-epilogue waits + L1 attention K/V tile-0 hoist
# speedup vs baseline: 1.0179x; 1.0127x over previous
; DI unsigned pack2(float lo, float hi) { const f32x2 v = (f32x2){lo, hi}; return __builtin_bit_cast(unsigned, __builtin_convertvector(v, bf16x2_t)); }
; DI void hgrn_scan_mfma(const Params& p, char* shm) {
;     ...
;             { const bf16_t* kt16 = (const bf16_t*)KtL; const bf16_t* v16 = (const bf16_t*)VL; const int vcol = w * 16 + l15;
;     ...
;               const bf16x8 vf = __builtin_bit_cast(bf16x8, (u32x4){HG_U2(v16, g * 4 + 0, g * 4 + 1, vcol), HG_U2(v16, g * 4 + 2, g * 4 + 3, vcol), HG_U2(v16, 16 + g * 4 + 0, 16 + g * 4 + 1, vcol), HG_U2(v16, 16 + g * 4 + 2, 16 + g * 4 + 3, vcol)});
;               f32x4 sc00 = (f32x4){0.f, 0.f, 0.f, 0.f}, sc01 = sc00, sc11 = sc00, o0 = sc00, o1 = sc00;
; #pragma unroll
;               for (int kc = 0; kc < 4; ++kc) {
;                   const bf16x8 aK0 = *(const bf16x8*)(KtL + l15 * QS + kc * 64 + g * 16), aK1 = *(const bf16x8*)(KtL + (16 + l15) * QS + kc * 64 + g * 16);
;                   const bf16x8 bQ0 = *(const bf16x8*)(QtL + l15 * QS + kc * 64 + g * 16), bQ1 = *(const bf16x8*)(QtL + (16 + l15) * QS + kc * 64 + g * 16);
;                   sc00 = __builtin_amdgcn_mfma_f32_16x16x32_bf16(aK0, bQ0, sc00, 0, 0, 0);
;                   sc01 = __builtin_amdgcn_mfma_f32_16x16x32_bf16(aK0, bQ1, sc01, 0, 0, 0);
;                   sc11 = __builtin_amdgcn_mfma_f32_16x16x32_bf16(aK1, bQ1, sc11, 0, 0, 0);
;                   const int kp = kc;
;                   const u32x2 qa0 = *(const u32x2*)(QtL + l15 * QS + ((2 * kp) * 16 + g * 4) * 2), qb0 = *(const u32x2*)(QtL + l15 * QS + ((2 * kp + 1) * 16 + g * 4) * 2);
;                   const u32x2 qa1 = *(const u32x2*)(QtL + (16 + l15) * QS + ((2 * kp) * 16 + g * 4) * 2), qb1 = *(const u32x2*)(QtL + (16 + l15) * QS + ((2 * kp + 1) * 16 + g * 4) * 2);
;                   const bf16x8 sw = __builtin_bit_cast(bf16x8, (u32x4){pack2(S[2 * kp][0], S[2 * kp][1]), pack2(S[2 * kp][2], S[2 * kp][3]), pack2(S[2 * kp + 1][0], S[2 * kp + 1][1]), pack2(S[2 * kp + 1][2], S[2 * kp + 1][3])});
;                   o0 = __builtin_amdgcn_mfma_f32_16x16x32_bf16(__builtin_bit_cast(bf16x8, (u32x4){qa0.x, qa0.y, qb0.x, qb0.y}), sw, o0, 0, 0, 0);
;                   o1 = __builtin_amdgcn_mfma_f32_16x16x32_bf16(__builtin_bit_cast(bf16x8, (u32x4){qa1.x, qa1.y, qb1.x, qb1.y}), sw, o1, 0, 0, 0); }
; #pragma unroll
;               for (int r = 0; r < 4; ++r) if (g * 4 + r > l15) { sc00[r] = 0.f; sc11[r] = 0.f; }
.LBB0_2441:
	v_mul_f32_e32 v58, v98, v58
	v_mul_f32_e32 v59, v99, v59
	v_mul_f32_e32 v56, v96, v56
	v_mul_f32_e32 v57, v97, v57
	ds_read_b128 v[96:99], v160 offset:50176
	v_mul_f32_e32 v62, v94, v62
	v_mul_f32_e32 v63, v95, v63
	v_mul_f32_e32 v60, v92, v60
	v_mul_f32_e32 v61, v93, v61
	ds_read_b128 v[68:71], v160 offset:54528
	ds_read_b128 v[92:95], v160 offset:32768
	v_mul_f32_e32 v46, v110, v46
	v_mul_f32_e32 v47, v111, v47
	v_mul_f32_e32 v44, v108, v44
	v_mul_f32_e32 v45, v109, v45
	v_mul_f32_e32 v50, v106, v50
	v_mul_f32_e32 v51, v107, v51
	v_mul_f32_e32 v48, v104, v48
	v_mul_f32_e32 v49, v105, v49
	v_mul_f32_e32 v54, v102, v54
	v_mul_f32_e32 v55, v103, v55
	v_mul_f32_e32 v52, v100, v52
	v_mul_f32_e32 v53, v101, v53
	ds_read_b128 v[100:103], v160 offset:37120
	ds_read_b128 v[104:107], v160 offset:50240
	ds_read_b128 v[108:111], v160 offset:32832
	ds_read_b128 v[162:165], v160 offset:54592
	ds_read_b128 v[166:169], v160 offset:37184
	v_mul_f32_e32 v66, v90, v66
	v_mul_f32_e32 v67, v91, v67
	s_waitcnt lgkmcnt(5)
	v_mfma_f32_16x16x32_bf16 v[90:93], v[96:99], v[92:95], 0
	v_mul_f32_e64 v64, v88, v64
	v_mul_f32_e64 v65, v89, v65
	v_mul_f32_e32 v78, v74, v78
	v_mul_f32_e32 v79, v75, v79
	v_mul_f32_e32 v76, v72, v76
	v_mul_f32_e32 v77, v73, v77
	s_waitcnt lgkmcnt(4)
	v_mfma_f32_16x16x32_bf16 v[170:173], v[68:71], v[100:103], 0
	v_mul_f32_e64 v70, v86, v82
	v_mul_f32_e64 v71, v87, v83
	v_mul_f32_e32 v68, v84, v80
	v_mul_f32_e32 v69, v85, v81
	ds_read_b128 v[84:87], v160 offset:50304
	s_waitcnt lgkmcnt(3)
	v_mfma_f32_16x16x32_bf16 v[80:83], v[104:107], v[108:111], v[90:93]
	s_nop 2
	ds_read_b128 v[88:91], v160 offset:54656
	ds_read_b128 v[92:95], v160 offset:32896
	v_cvt_pk_bf16_f32 v186, v52, v53
	v_cvt_pk_bf16_f32 v187, v54, v55
	s_waitcnt lgkmcnt(3)
	v_mfma_f32_16x16x32_bf16 v[108:111], v[162:165], v[166:169], v[170:173]
	ds_read_b128 v[162:165], v160 offset:37248
	s_nop 1
	ds_read_b128 v[170:173], v160 offset:50368
	ds_read_b128 v[174:177], v160 offset:32960
	ds_read_b128 v[72:75], v160 offset:54720
	ds_read_b128 v[178:181], v160 offset:37312
	v_cvt_pk_bf16_f32 v188, v56, v57
	s_waitcnt lgkmcnt(4)
	v_mfma_f32_16x16x32_bf16 v[88:91], v[88:91], v[162:165], v[108:111]
	v_cvt_pk_bf16_f32 v189, v58, v59
	s_add_i32 s14, s74, 32
	s_and_b64 s[0:1], s[12:13], exec
	v_mfma_f32_16x16x32_bf16 v[92:95], v[84:87], v[92:95], v[80:83]
	ds_read_b64_tr_b16 v[80:81], v198 offset:41472
	ds_read_b64_tr_b16 v[82:83], v198 offset:45824
	ds_read2_b64 v[108:111], v195 offset1:4
	s_waitcnt lgkmcnt(3)
	v_mfma_f32_16x16x32_bf16 v[72:75], v[72:75], v[178:181], v[88:91]
	v_mov_b32_e32 v0, s39
	ds_read2_b64 v[88:91], v197 offset0:32 offset1:36
	v_mfma_f32_16x16x32_bf16 v[96:99], v[96:99], v[100:103], 0
	s_cselect_b32 s0, s14, s77
	s_add_u32 s0, s50, s0
	v_mfma_f32_16x16x32_bf16 v[92:95], v[170:173], v[174:177], v[92:95]
	v_cvt_pk_bf16_f32 v174, v44, v45
	v_cvt_pk_bf16_f32 v175, v46, v47
	v_cvt_pk_bf16_f32 v176, v48, v49
	v_cvt_pk_bf16_f32 v177, v50, v51
	v_mfma_f32_16x16x32_bf16 v[96:99], v[104:107], v[166:169], v[96:99]
	s_nop 2
	v_cndmask_b32_e64 v0, v92, v0, s[4:5]
	v_cndmask_b32_e64 v0, v0, v92, s[6:7]
	v_cndmask_b32_e64 v3, v94, 0, s[8:9]
	s_waitcnt lgkmcnt(1)
	v_mfma_f32_16x16x32_bf16 v[100:103], v[108:111], v[174:177], 0
	ds_read2_b64 v[108:111], v195 offset0:8 offset1:12
	ds_read2_b64 v[182:185], v197 offset0:40 offset1:44
	ds_read2_b64 v[104:107], v195 offset0:16 offset1:20
	ds_read2_b64 v[166:169], v197 offset0:48 offset1:52
	s_addc_u32 s1, s51, 0
	s_waitcnt lgkmcnt(4)
	v_mfma_f32_16x16x32_bf16 v[88:91], v[88:91], v[174:177], 0
	v_cvt_pk_bf16_f32 v174, v60, v61
	v_cvt_pk_bf16_f32 v175, v62, v63
	v_cvt_pk_bf16_f32 v176, v64, v65
	s_waitcnt lgkmcnt(3)
	v_mfma_f32_16x16x32_bf16 v[100:103], v[108:111], v[186:189], v[100:103]
	v_cvt_pk_bf16_f32 v177, v66, v67
	s_lshl_b64 s[0:1], s[0:1], 11
	v_mfma_f32_16x16x32_bf16 v[84:87], v[84:87], v[162:165], v[96:99]
	s_sub_i32 s38, s38, 64
	s_add_i32 s74, s74, 64
	s_and_b64 vcc, exec, s[54:55]
	s_waitcnt lgkmcnt(2)
	v_mfma_f32_16x16x32_bf16 v[88:91], v[182:185], v[186:189], v[88:91]
	ds_read2_b64 v[108:111], v195 offset0:24 offset1:28
	ds_read2_b64 v[182:185], v197 offset0:56 offset1:60
	v_cvt_pk_bf16_f32 v186, v68, v69
	v_cvt_pk_bf16_f32 v187, v70, v71
	s_waitcnt lgkmcnt(3)
	v_mfma_f32_16x16x32_bf16 v[96:99], v[104:107], v[174:177], v[100:103]
	v_cvt_pk_bf16_f32 v188, v76, v77
	v_cvt_pk_bf16_f32 v189, v78, v79
	s_nop 0
	v_mov_b32_e32 v100, s39
	v_mfma_f32_16x16x32_bf16 v[84:87], v[170:173], v[178:181], v[84:87]
	v_cndmask_b32_e64 v1, v72, v100, s[4:5]
	v_cndmask_b32_e64 v100, v1, v72, s[6:7]
	v_cndmask_b32_e64 v1, 0, v93, s[6:7]
	s_waitcnt lgkmcnt(2)
; DI unsigned pack2(float lo, float hi) { const f32x2 v = (f32x2){lo, hi}; return __builtin_bit_cast(unsigned, __builtin_convertvector(v, bf16x2_t)); }
; DI void hgrn_scan_mfma(const Params& p, char* shm) {
;     ...
;               o0 = __builtin_amdgcn_mfma_f32_16x16x32_bf16(__builtin_bit_cast(bf16x8, (u32x4){pack2(sc00[0], sc00[1]), pack2(sc00[2], sc00[3]), 0u, 0u}), vf, o0, 0, 0, 0);
;               o1 = __builtin_amdgcn_mfma_f32_16x16x32_bf16(__builtin_bit_cast(bf16x8, (u32x4){pack2(sc01[0], sc01[1]), pack2(sc01[2], sc01[3]), pack2(sc11[0], sc11[1]), pack2(sc11[2], sc11[3])}), vf, o1, 0, 0, 0);
; #pragma unroll
;               for (int r = 0; r < 4; ++r) {
;                   const long rb_ = (long)HG_ROW(b, dir, ch * C), st_ = dir ? -(long)D : (long)D; bf16_t* op_ = Oo + rb_ * D + head * 128 + vcol + (long)(g * 4 + r) * st_;
;                   op_[0] = (bf16_t)(pack2(o0[r], 0.f) & 0xffffu); op_[16 * st_] = (bf16_t)(pack2(o1[r], 0.f) & 0xffffu); }
; #pragma unroll
;               for (int kt = 0; kt < 8; ++kt) { const f32x4 dcy = *(const f32x4*)(eBL + kt * 16 + g * 4); const int kcol = kt * 16 + l15;
;                   const bf16x8 kl = __builtin_bit_cast(bf16x8, (u32x4){HG_U2(kt16, g * 4 + 0, g * 4 + 1, kcol), HG_U2(kt16, g * 4 + 2, g * 4 + 3, kcol), HG_U2(kt16, 16 + g * 4 + 0, 16 + g * 4 + 1, kcol), HG_U2(kt16, 16 + g * 4 + 2, 16 + g * 4 + 3, kcol)});
;                   S[kt] = __builtin_amdgcn_mfma_f32_16x16x32_bf16(kl, vf, S[kt], 0, 0, 0) * dcy; }
	v_mfma_f32_16x16x32_bf16 v[88:91], v[166:169], v[174:177], v[88:91]
	v_cndmask_b32_e64 v72, v95, 0, s[10:11]
	v_cvt_pk_bf16_f32 v0, v0, v1
	v_cvt_pk_bf16_f32 v1, v3, v72
	s_waitcnt lgkmcnt(1)
	v_mfma_f32_16x16x32_bf16 v[92:95], v[108:111], v[186:189], v[96:99]
	v_mov_b32_e32 v3, v2
	v_cvt_pk_bf16_f32 v84, v84, v85
	v_cvt_pk_bf16_f32 v85, v86, v87
	v_cndmask_b32_e64 v96, 0, v73, s[6:7]
	v_cndmask_b32_e64 v97, v74, 0, s[8:9]
	v_cndmask_b32_e64 v98, v75, 0, s[10:11]
	v_cvt_pk_bf16_f32 v86, v100, v96
	v_cvt_pk_bf16_f32 v87, v97, v98
	s_waitcnt lgkmcnt(0)
	v_mfma_f32_16x16x32_bf16 v[88:91], v[182:185], v[186:189], v[88:91]
	v_mfma_f32_16x16x32_bf16 v[72:75], v[0:3], v[80:83], v[92:95]
	v_lshl_add_u64 v[0:1], v[132:133], 0, s[0:1]
	v_mfma_f32_16x16x32_bf16 v[84:87], v[84:87], v[80:83], v[88:91]
	s_nop 4
	v_lshl_add_u64 v[88:89], v[134:135], 1, v[0:1]
	v_cvt_pk_bf16_f32 v3, v72, s0
	global_store_short v[88:89], v3, off
	v_cvt_pk_bf16_f32 v3, v84, s0
	v_lshl_add_u64 v[88:89], v[88:89], 0, s[52:53]
	global_store_short v[88:89], v3, off
	v_lshl_add_u64 v[88:89], v[136:137], 1, v[0:1]
	v_cvt_pk_bf16_f32 v3, v73, s0
	global_store_short v[88:89], v3, off
	v_cvt_pk_bf16_f32 v3, v85, s0
	v_lshl_add_u64 v[72:73], v[88:89], 0, s[52:53]
	global_store_short v[72:73], v3, off
	v_lshl_add_u64 v[72:73], v[138:139], 1, v[0:1]
	v_cvt_pk_bf16_f32 v3, v74, s0
	global_store_short v[72:73], v3, off
	v_cvt_pk_bf16_f32 v3, v86, s0
	v_lshl_add_u64 v[72:73], v[72:73], 0, s[52:53]
	global_store_short v[72:73], v3, off
	v_lshl_add_u64 v[0:1], v[140:141], 1, v[0:1]
	v_cvt_pk_bf16_f32 v3, v75, s0
	global_store_short v[0:1], v3, off
	v_cvt_pk_bf16_f32 v3, v87, s0
	v_lshl_add_u64 v[0:1], v[0:1], 0, s[52:53]
	global_store_short v[0:1], v3, off
	ds_read_b128 v[72:75], v149 offset:58880
	ds_read_b64_tr_b16 v[200:201], v199 offset:50176
	ds_read_b64_tr_b16 v[202:203], v199 offset:54528
	ds_read_b64_tr_b16 v[204:205], v199 offset:50208
	ds_read_b64_tr_b16 v[206:207], v199 offset:54560
	ds_read_b64_tr_b16 v[208:209], v199 offset:50240
	ds_read_b64_tr_b16 v[210:211], v199 offset:54592
	ds_read_b64_tr_b16 v[212:213], v199 offset:50272
	ds_read_b64_tr_b16 v[214:215], v199 offset:54624
	ds_read_b64_tr_b16 v[216:217], v199 offset:50304
	ds_read_b64_tr_b16 v[218:219], v199 offset:54656
	ds_read_b64_tr_b16 v[220:221], v199 offset:50336
	ds_read_b64_tr_b16 v[222:223], v199 offset:54688
	ds_read_b64_tr_b16 v[224:225], v199 offset:50368
	ds_read_b64_tr_b16 v[226:227], v199 offset:54720
	ds_read_b64_tr_b16 v[228:229], v199 offset:50400
	ds_read_b64_tr_b16 v[230:231], v199 offset:54752
	s_waitcnt lgkmcnt(14)
	v_mfma_f32_16x16x32_bf16 v[44:47], v[200:203], v[80:83], v[44:47]
	ds_read_b128 v[84:87], v149 offset:58944
	s_waitcnt lgkmcnt(13)
	v_mfma_f32_16x16x32_bf16 v[48:51], v[204:207], v[80:83], v[48:51]
	s_nop 4
	v_mul_f32_e32 v46, v74, v46
	v_mul_f32_e32 v47, v75, v47
	v_mul_f32_e32 v44, v72, v44
	v_mul_f32_e32 v45, v73, v45
	ds_read_b128 v[72:75], v149 offset:59008
	s_waitcnt lgkmcnt(1)
	v_mul_f32_e32 v50, v86, v50
	v_mul_f32_e32 v51, v87, v51
	v_mul_f32_e32 v48, v84, v48
	v_mul_f32_e32 v49, v85, v49
	v_mfma_f32_16x16x32_bf16 v[52:55], v[208:211], v[80:83], v[52:55]
	ds_read_b128 v[84:87], v149 offset:59072
	v_mfma_f32_16x16x32_bf16 v[56:59], v[212:215], v[80:83], v[56:59]
	s_nop 4
	s_waitcnt lgkmcnt(1)
	v_mul_f32_e32 v54, v74, v54
	v_mul_f32_e32 v55, v75, v55
	v_mul_f32_e32 v52, v72, v52
	v_mul_f32_e32 v53, v73, v53
	ds_read_b128 v[72:75], v149 offset:59136
	s_waitcnt lgkmcnt(1)
	v_mul_f32_e32 v58, v86, v58
	v_mul_f32_e32 v59, v87, v59
	v_mul_f32_e32 v56, v84, v56
	v_mul_f32_e32 v57, v85, v57
	v_mfma_f32_16x16x32_bf16 v[60:63], v[216:219], v[80:83], v[60:63]
	ds_read_b128 v[84:87], v149 offset:59200
	v_mfma_f32_16x16x32_bf16 v[64:67], v[220:223], v[80:83], v[64:67]
	s_nop 4
	s_waitcnt lgkmcnt(1)
	v_mul_f32_e32 v62, v74, v62
	v_mul_f32_e32 v63, v75, v63
	v_mul_f32_e32 v60, v72, v60
	v_mul_f32_e32 v61, v73, v61
	ds_read_b128 v[72:75], v149 offset:59264
	s_waitcnt lgkmcnt(1)
	v_mul_f32_e32 v66, v86, v66
	v_mul_f32_e32 v67, v87, v67
	v_mul_f32_e32 v64, v84, v64
	v_mul_f32_e32 v65, v85, v65
	v_mfma_f32_16x16x32_bf16 v[68:71], v[224:227], v[80:83], v[68:71]
	ds_read_b128 v[84:87], v149 offset:59328
	s_nop 5
	s_waitcnt lgkmcnt(1)
	v_mul_f32_e32 v74, v74, v70
	v_mul_f32_e32 v75, v75, v71
	v_mul_f32_e32 v72, v72, v68
	v_mul_f32_e32 v73, v73, v69
	v_mfma_f32_16x16x32_bf16 v[68:71], v[228:231], v[80:83], v[76:79]
	s_nop 6
	s_waitcnt lgkmcnt(0)
	v_mul_f32_e32 v70, v86, v70
	v_mul_f32_e32 v71, v87, v71
	v_mul_f32_e32 v68, v84, v68
	v_mul_f32_e32 v69, v85, v69
	s_cbranch_vccnz .LBB0_2411
	s_mov_b32 s76, s75
	s_branch .LBB0_2417

.Lscanh_loop:
	s_waitcnt vmcnt(8)
	v_lshlrev_b32_e32 v80, 16, v12
	v_and_b32_e32 v81, 0xffff0000, v12
	v_lshlrev_b32_e32 v82, 16, v16
	v_and_b32_e32 v83, 0xffff0000, v16
	v_lshlrev_b32_e32 v84, 16, v13
	v_and_b32_e32 v85, 0xffff0000, v13
	v_lshlrev_b32_e32 v86, 16, v17
	v_and_b32_e32 v87, 0xffff0000, v17
	v_mul_f32_e32 v80, v80, v82
	v_mul_f32_e32 v81, v81, v83
	v_mul_f32_e32 v84, v84, v86
	v_mul_f32_e32 v85, v85, v87
	v_cvt_pk_bf16_f32 v76, v80, v81
	v_cvt_pk_bf16_f32 v77, v84, v85
	v_lshlrev_b32_e32 v80, 16, v14
	v_and_b32_e32 v81, 0xffff0000, v14
	v_lshlrev_b32_e32 v82, 16, v18
	v_and_b32_e32 v83, 0xffff0000, v18
	v_lshlrev_b32_e32 v84, 16, v15
	v_and_b32_e32 v85, 0xffff0000, v15
	v_lshlrev_b32_e32 v86, 16, v19
	v_and_b32_e32 v87, 0xffff0000, v19
	v_mul_f32_e32 v80, v80, v82
	v_mul_f32_e32 v81, v81, v83
	v_mul_f32_e32 v84, v84, v86
	v_mul_f32_e32 v85, v85, v87
	v_cvt_pk_bf16_f32 v78, v80, v81
	v_cvt_pk_bf16_f32 v79, v84, v85
	v_lshlrev_b32_e32 v80, 16, v196
	v_and_b32_e32 v81, 0xffff0000, v196
	v_lshlrev_b32_e32 v82, 16, v200
	v_and_b32_e32 v83, 0xffff0000, v200
	v_lshlrev_b32_e32 v84, 16, v197
	v_and_b32_e32 v85, 0xffff0000, v197
	v_lshlrev_b32_e32 v86, 16, v201
	v_and_b32_e32 v87, 0xffff0000, v201
	v_mul_f32_e32 v80, v80, v82
	v_mul_f32_e32 v81, v81, v83
	v_mul_f32_e32 v84, v84, v86
	v_mul_f32_e32 v85, v85, v87
	v_cvt_pk_bf16_f32 v246, v80, v81
	v_cvt_pk_bf16_f32 v247, v84, v85
	v_lshlrev_b32_e32 v80, 16, v198
	v_and_b32_e32 v81, 0xffff0000, v198
	v_lshlrev_b32_e32 v82, 16, v202
	v_and_b32_e32 v83, 0xffff0000, v202
	v_lshlrev_b32_e32 v84, 16, v199
	v_and_b32_e32 v85, 0xffff0000, v199
	v_lshlrev_b32_e32 v86, 16, v203
	v_and_b32_e32 v87, 0xffff0000, v203
	v_mul_f32_e32 v80, v80, v82
	v_mul_f32_e32 v81, v81, v83
	v_mul_f32_e32 v84, v84, v86
	v_mul_f32_e32 v85, v85, v87
	v_cvt_pk_bf16_f32 v248, v80, v81
	v_cvt_pk_bf16_f32 v249, v84, v85
	ds_write_b128 v158, v[76:79]
	ds_write_b128 v158, v[20:23] offset:8704
	ds_write_b128 v158, v[24:27] offset:17408
	ds_write_b128 v228, v[246:249]
	ds_write_b128 v228, v[204:207] offset:8704
	ds_write_b128 v228, v[208:211] offset:17408
	s_and_saveexec_b64 s[14:15], s[2:3]
	ds_write_b128 v229, v[4:7] offset:26112
	s_or_b64 exec, exec, s[14:15]
	s_add_i32 s75, s76, 2
	s_cmpk_lt_u32 s76, 0x46
	s_cselect_b64 s[56:57], -1, 0
	s_cmpk_gt_u32 s76, 0x45
	s_cselect_b64 s[54:55], -1, 0
	s_waitcnt lgkmcnt(0)
	s_barrier
	s_and_b64 vcc, exec, s[54:55]
	s_cbranch_vccnz .Lscanh_nopfa
	s_and_b64 vcc, exec, s[12:13]
	v_lshl_add_u32 v0, s75, 5, v113
	s_cbranch_vccnz .Lscanh_ia
	v_add3_u32 v1, v113, s74, 64
	v_cmp_lt_i32_e32 vcc, s47, v1
	s_and_saveexec_b64 s[14:15], vcc
	s_xor_b64 s[14:15], exec, s[14:15]
	v_add_u32_e32 v0, s38, v156
	v_add_u32_e32 v0, 0x9df, v0
	s_andn2_saveexec_b64 s[14:15], s[14:15]
	v_sub_u32_e32 v0, 0xff, v0
	s_or_b64 exec, exec, s[14:15]

.Lscanh_steady:
	s_waitcnt vmcnt(8)
	v_lshlrev_b32_e32 v80, 16, v28
	v_and_b32_e32 v81, 0xffff0000, v28
	v_lshlrev_b32_e32 v82, 16, v32
	v_and_b32_e32 v83, 0xffff0000, v32
	v_lshlrev_b32_e32 v84, 16, v29
	v_and_b32_e32 v85, 0xffff0000, v29
	v_lshlrev_b32_e32 v86, 16, v33
	v_and_b32_e32 v87, 0xffff0000, v33
	v_mul_f32_e32 v80, v80, v82
	v_mul_f32_e32 v81, v81, v83
	v_mul_f32_e32 v84, v84, v86
	v_mul_f32_e32 v85, v85, v87
	v_cvt_pk_bf16_f32 v68, v80, v81
	v_cvt_pk_bf16_f32 v69, v84, v85
	v_lshlrev_b32_e32 v80, 16, v30
	v_and_b32_e32 v81, 0xffff0000, v30
	v_lshlrev_b32_e32 v82, 16, v34
	v_and_b32_e32 v83, 0xffff0000, v34
	v_lshlrev_b32_e32 v84, 16, v31
	v_and_b32_e32 v85, 0xffff0000, v31
	v_lshlrev_b32_e32 v86, 16, v35
	v_and_b32_e32 v87, 0xffff0000, v35
	v_mul_f32_e32 v80, v80, v82
	v_mul_f32_e32 v81, v81, v83
	v_mul_f32_e32 v84, v84, v86
	v_mul_f32_e32 v85, v85, v87
	v_cvt_pk_bf16_f32 v70, v80, v81
	v_cvt_pk_bf16_f32 v71, v84, v85
	v_lshlrev_b32_e32 v80, 16, v212
	v_and_b32_e32 v81, 0xffff0000, v212
	v_lshlrev_b32_e32 v82, 16, v216
	v_and_b32_e32 v83, 0xffff0000, v216
	v_lshlrev_b32_e32 v84, 16, v213
	v_and_b32_e32 v85, 0xffff0000, v213
	v_lshlrev_b32_e32 v86, 16, v217
	v_and_b32_e32 v87, 0xffff0000, v217
	v_mul_f32_e32 v80, v80, v82
	v_mul_f32_e32 v81, v81, v83
	v_mul_f32_e32 v84, v84, v86
	v_mul_f32_e32 v85, v85, v87
	v_cvt_pk_bf16_f32 v246, v80, v81
	v_cvt_pk_bf16_f32 v247, v84, v85
	v_lshlrev_b32_e32 v80, 16, v214
	v_and_b32_e32 v81, 0xffff0000, v214
	v_lshlrev_b32_e32 v82, 16, v218
	v_and_b32_e32 v83, 0xffff0000, v218
	v_lshlrev_b32_e32 v84, 16, v215
	v_and_b32_e32 v85, 0xffff0000, v215
	v_lshlrev_b32_e32 v86, 16, v219
	v_and_b32_e32 v87, 0xffff0000, v219
	v_mul_f32_e32 v80, v80, v82
	v_mul_f32_e32 v81, v81, v83
	v_mul_f32_e32 v84, v84, v86
	v_mul_f32_e32 v85, v85, v87
	v_cvt_pk_bf16_f32 v248, v80, v81
	v_cvt_pk_bf16_f32 v249, v84, v85
	ds_write_b128 v158, v[68:71] offset:32768
	ds_write_b128 v158, v[36:39] offset:41472
	ds_write_b128 v158, v[40:43] offset:50176
	ds_write_b128 v228, v[246:249] offset:32768
	ds_write_b128 v228, v[220:223] offset:41472
	ds_write_b128 v228, v[224:227] offset:50176
	s_and_saveexec_b64 s[14:15], s[2:3]
	ds_write_b128 v229, v[8:11] offset:58880
	s_or_b64 exec, exec, s[14:15]
	s_waitcnt lgkmcnt(0)
	s_barrier
	s_andn2_b64 vcc, exec, s[56:57]
	s_cbranch_vccnz .Lscanh_nopfb
	s_lshl_b32 s14, s76, 5
	s_addk_i32 s14, 0x60
	s_and_b64 vcc, exec, s[12:13]
	v_add_u32_e32 v0, s14, v113
	s_cbranch_vccnz .Lscanh_ib
	v_add_u32_e32 v1, s74, v113
	v_add_u32_e32 v1, 0x60, v1
	v_cmp_lt_i32_e32 vcc, s47, v1
	s_and_saveexec_b64 s[14:15], vcc
	s_xor_b64 s[14:15], exec, s[14:15]
	v_add_u32_e32 v0, s38, v156
	v_add_u32_e32 v0, 0x9bf, v0
	s_andn2_saveexec_b64 s[14:15], s[14:15]
	v_sub_u32_e32 v0, 0xff, v0
	s_or_b64 exec, exec, s[14:15]
